# merged vmcnt(8)+lgkmcnt(0) into one wait before each K-loop barrier
# speedup vs baseline: 1.0014x; 1.0002x over previous
; #define PG8_STAGE(bufoff, gbase, voff) do { _Pragma("unroll") for (int _i = 0; _i < 2; ++_i) \
;         __builtin_amdgcn_global_load_lds((const unsigned*)((const char*)(gbase) + (voff)[_i]), (PG8_LAS unsigned*)(lds + (bufoff) + ldsw + _i * 8192), 16, 0, 0); } while (0)
; #define PG8_LDA(dst, b, h) do { _Pragma("unroll") for (int m = 0; m < 4; ++m) _Pragma("unroll") for (int k = 0; k < 2; ++k) dst[m][k] = *(const PG8_LAS bf16x8*)(lds + PG8_SA(b, h) + aoff + m * 2048 + k * 1024); } while (0)
; #define PG8_LDB(dst, b, h) do { _Pragma("unroll") for (int n = 0; n < 2; ++n) _Pragma("unroll") for (int k = 0; k < 2; ++k) dst[n][k] = *(const PG8_LAS bf16x8*)(lds + PG8_SB(b, h) + boff + n * 2048 + k * 1024); } while (0)
; #define PG8_MMA(ai, bj, At, Bt) do { __builtin_amdgcn_s_setprio(1); _Pragma("unroll") for (int m = 0; m < 4; ++m) _Pragma("unroll") for (int n = 0; n < 2; ++n) _Pragma("unroll") for (int k = 0; k < 2; ++k) \
;         acc[ai][bj][m][n] = __builtin_amdgcn_mfma_f32_16x16x32_bf16(Bt[n][k], At[m][k], acc[ai][bj][m][n], 0, 0, 0); __builtin_amdgcn_s_setprio(0); } while (0)
; #define PG8_WAIT_V(n) asm volatile("s_waitcnt vmcnt(" #n ")" ::: "memory")
; #define PG8_WAIT_L(n) asm volatile("s_waitcnt lgkmcnt(" #n ")" ::: "memory")
; #define PG8_BAR __builtin_amdgcn_s_barrier()
; #define PG8_SCHED __builtin_amdgcn_sched_barrier(0)
; template <class Epi, class Sched, bool ALIGN_EPI = false, bool SP2 = false>
; __device__ __forceinline__ void gemm_phase(PG8_LAS unsigned char* lds, const Gemm g, const Sched& S, const Epi& E) {
;     ...
;             const bool last = (t == nt - 2);
;             const char* a1 = cA + (size_t)(t + 1) * kstep;
;             const char* a2 = last ? nA : cA + (size_t)(t + 2) * kstep; const char* b2 = last ? nB : cB + (size_t)(t + 2) * kstep;
;             const char* a3 = a2 + kstep; const char* b3 = b2 + kstep;
;             if (last && has_next) S.a_ready(nxt);
;             if constexpr (SP2) {
;             PG8_LDB(B0, 0, 0); PG8_LDB(B1, 0, 1); PG8_SCHED; PG8_LDA(At, 0, 0); PG8_STAGE(PG8_SA(1, 1), a1 + hstep, voffA);
;             PG8_WAIT_V(8); PG8_WAIT_L(0); PG8_BAR; PG8_MMA(0, 0, At, B0); PG8_MMA(0, 1, At, B1); PG8_BAR; PG8_SCHED;
;             PG8_LDA(At, 0, 1); PG8_STAGE(PG8_SB(0, 0), b2, voffB); PG8_STAGE(PG8_SB(0, 1), b2 + hstep, voffB); PG8_STAGE(PG8_SA(0, 0), a2, voffA);
.LBB0_441:
	s_add_i32 s61, s44, 2
	s_add_u32 s64, s42, 0x80
	s_addc_u32 s45, s43, 0
	s_add_i32 s66, 0, 0x10000
	s_cmp_eq_u32 s99, s44
	s_cselect_b32 s45, s29, s45
	s_cselect_b32 s44, s28, s64
	s_cselect_b32 s65, s21, s60
	s_cselect_b32 s64, s20, s17
	s_add_i32 s67, 0, 0x14000
	v_add_u32_e32 v142, s66, v228
	v_add_u32_e32 v158, s67, v228
	ds_read_b128 v[130:133], v142
	ds_read_b128 v[134:137], v142 offset:1024
	ds_read_b128 v[138:141], v142 offset:2048
	ds_read_b128 v[142:145], v142 offset:3072
	ds_read_b128 v[146:149], v158
	ds_read_b128 v[150:153], v158 offset:1024
	ds_read_b128 v[154:157], v158 offset:2048
	ds_read_b128 v[158:161], v158 offset:3072
	v_lshl_add_u64 v[206:207], s[42:43], 0, v[190:191]
	s_add_i32 m0, s93, 0xc000
	ds_read_b128 v[162:165], v230
	ds_read_b128 v[166:169], v230 offset:1024
	ds_read_b128 v[170:173], v230 offset:2048
	ds_read_b128 v[174:177], v230 offset:3072
	ds_read_b128 v[178:181], v230 offset:4096
	ds_read_b128 v[194:197], v230 offset:5120
	ds_read_b128 v[198:201], v230 offset:6144
	ds_read_b128 v[202:205], v230 offset:7168
	global_load_lds_dwordx4 v[206:207], off
	v_lshl_add_u64 v[206:207], s[42:43], 0, v[192:193]
	s_add_i32 m0, s93, 0xe000
	s_nop 0
	global_load_lds_dwordx4 v[206:207], off
	s_waitcnt vmcnt(8) lgkmcnt(0)
	s_barrier
	s_setprio 1
	v_mfma_f32_16x16x32_bf16 v[126:129], v[130:133], v[162:165], v[126:129]
	v_mfma_f32_16x16x32_bf16 v[122:125], v[138:141], v[162:165], v[122:125]
	v_mfma_f32_16x16x32_bf16 v[110:113], v[130:133], v[170:173], v[110:113]
	v_mfma_f32_16x16x32_bf16 v[102:105], v[138:141], v[170:173], v[102:105]
	v_mfma_f32_16x16x32_bf16 v[94:97], v[130:133], v[178:181], v[94:97]
	v_mfma_f32_16x16x32_bf16 v[86:89], v[138:141], v[178:181], v[86:89]
	v_mfma_f32_16x16x32_bf16 v[78:81], v[130:133], v[198:201], v[78:81]
	v_mfma_f32_16x16x32_bf16 v[70:73], v[138:141], v[198:201], v[70:73]
	v_mfma_f32_16x16x32_bf16 v[126:129], v[134:137], v[166:169], v[126:129]
	v_mfma_f32_16x16x32_bf16 v[122:125], v[142:145], v[166:169], v[122:125]
	v_mfma_f32_16x16x32_bf16 v[110:113], v[134:137], v[174:177], v[110:113]
	v_mfma_f32_16x16x32_bf16 v[102:105], v[142:145], v[174:177], v[102:105]
	v_mfma_f32_16x16x32_bf16 v[94:97], v[134:137], v[194:197], v[94:97]
	v_mfma_f32_16x16x32_bf16 v[86:89], v[142:145], v[194:197], v[86:89]
	v_mfma_f32_16x16x32_bf16 v[78:81], v[134:137], v[202:205], v[78:81]
	v_mfma_f32_16x16x32_bf16 v[70:73], v[142:145], v[202:205], v[70:73]
	s_setprio 0
	s_setprio 1
	v_mfma_f32_16x16x32_bf16 v[118:121], v[146:149], v[162:165], v[118:121]
	v_mfma_f32_16x16x32_bf16 v[114:117], v[154:157], v[162:165], v[114:117]
	v_mfma_f32_16x16x32_bf16 v[106:109], v[146:149], v[170:173], v[106:109]
	v_mfma_f32_16x16x32_bf16 v[98:101], v[154:157], v[170:173], v[98:101]
	v_mfma_f32_16x16x32_bf16 v[90:93], v[146:149], v[178:181], v[90:93]
	v_mfma_f32_16x16x32_bf16 v[82:85], v[154:157], v[178:181], v[82:85]
	v_mfma_f32_16x16x32_bf16 v[74:77], v[146:149], v[198:201], v[74:77]
	v_mfma_f32_16x16x32_bf16 v[66:69], v[154:157], v[198:201], v[66:69]
	v_mfma_f32_16x16x32_bf16 v[118:121], v[150:153], v[166:169], v[118:121]
	v_mfma_f32_16x16x32_bf16 v[114:117], v[158:161], v[166:169], v[114:117]
	v_mfma_f32_16x16x32_bf16 v[106:109], v[150:153], v[174:177], v[106:109]
	v_mfma_f32_16x16x32_bf16 v[98:101], v[158:161], v[174:177], v[98:101]
	v_mfma_f32_16x16x32_bf16 v[90:93], v[150:153], v[194:197], v[90:93]
	v_mfma_f32_16x16x32_bf16 v[82:85], v[158:161], v[194:197], v[82:85]
	v_mfma_f32_16x16x32_bf16 v[74:77], v[150:153], v[202:205], v[74:77]
	v_mfma_f32_16x16x32_bf16 v[66:69], v[158:161], v[202:205], v[66:69]
	s_setprio 0
	s_barrier
	s_add_i32 s66, s66, s92
	v_lshl_add_u64 v[206:207], s[64:65], 0, v[184:185]
	s_mov_b32 m0, s66
	ds_read_b128 v[162:165], v230 offset:16384
	ds_read_b128 v[166:169], v230 offset:17408
	ds_read_b128 v[170:173], v230 offset:18432
	ds_read_b128 v[174:177], v230 offset:19456
	ds_read_b128 v[178:181], v230 offset:20480
	ds_read_b128 v[194:197], v230 offset:21504
	ds_read_b128 v[198:201], v230 offset:22528
	ds_read_b128 v[202:205], v230 offset:23552
	global_load_lds_dwordx4 v[206:207], off
	s_add_i32 m0, s66, 0x2000
	v_lshl_add_u64 v[208:209], s[64:65], 0, v[188:189]
	s_add_u32 s64, s64, s26
	s_addc_u32 s65, s65, 0
	s_add_i32 s66, s67, s92
	global_load_lds_dwordx4 v[208:209], off
	v_lshl_add_u64 v[210:211], s[64:65], 0, v[184:185]
	s_mov_b32 m0, s66
	v_lshl_add_u64 v[232:233], s[64:65], 0, v[188:189]
	global_load_lds_dwordx4 v[210:211], off
	s_add_i32 m0, s66, 0x2000
	v_lshl_add_u64 v[234:235], s[44:45], 0, v[182:183]
	global_load_lds_dwordx4 v[232:233], off
	s_mov_b32 m0, s93
	v_lshl_add_u64 v[236:237], s[44:45], 0, v[186:187]
	global_load_lds_dwordx4 v[234:235], off
	s_mov_b32 m0, s94
	s_nop 0
	global_load_lds_dwordx4 v[236:237], off
	s_waitcnt vmcnt(8) lgkmcnt(0)
	s_barrier
; #define PG8_STAGE(bufoff, gbase, voff) do { _Pragma("unroll") for (int _i = 0; _i < 2; ++_i) \
;         __builtin_amdgcn_global_load_lds((const unsigned*)((const char*)(gbase) + (voff)[_i]), (PG8_LAS unsigned*)(lds + (bufoff) + ldsw + _i * 8192), 16, 0, 0); } while (0)
; #define PG8_LDA(dst, b, h) do { _Pragma("unroll") for (int m = 0; m < 4; ++m) _Pragma("unroll") for (int k = 0; k < 2; ++k) dst[m][k] = *(const PG8_LAS bf16x8*)(lds + PG8_SA(b, h) + aoff + m * 2048 + k * 1024); } while (0)
; #define PG8_LDB(dst, b, h) do { _Pragma("unroll") for (int n = 0; n < 2; ++n) _Pragma("unroll") for (int k = 0; k < 2; ++k) dst[n][k] = *(const PG8_LAS bf16x8*)(lds + PG8_SB(b, h) + boff + n * 2048 + k * 1024); } while (0)
; #define PG8_MMA(ai, bj, At, Bt) do { __builtin_amdgcn_s_setprio(1); _Pragma("unroll") for (int m = 0; m < 4; ++m) _Pragma("unroll") for (int n = 0; n < 2; ++n) _Pragma("unroll") for (int k = 0; k < 2; ++k) \
;         acc[ai][bj][m][n] = __builtin_amdgcn_mfma_f32_16x16x32_bf16(Bt[n][k], At[m][k], acc[ai][bj][m][n], 0, 0, 0); __builtin_amdgcn_s_setprio(0); } while (0)
; #define PG8_WAIT_V(n) asm volatile("s_waitcnt vmcnt(" #n ")" ::: "memory")
; #define PG8_WAIT_L(n) asm volatile("s_waitcnt lgkmcnt(" #n ")" ::: "memory")
; #define PG8_BAR __builtin_amdgcn_s_barrier()
; #define PG8_SCHED __builtin_amdgcn_sched_barrier(0)
; template <class Epi, class Sched, bool ALIGN_EPI = false, bool SP2 = false>
; __device__ __forceinline__ void gemm_phase(PG8_LAS unsigned char* lds, const Gemm g, const Sched& S, const Epi& E) {
;     ...
;             PG8_WAIT_V(8); PG8_WAIT_L(0); PG8_BAR; PG8_MMA(1, 0, At, B0); PG8_MMA(1, 1, At, B1); PG8_BAR; PG8_SCHED;
;             PG8_LDB(B0, 1, 0); PG8_LDB(B1, 1, 1); PG8_SCHED; PG8_LDA(At, 1, 0); PG8_STAGE(PG8_SA(0, 1), a2 + hstep, voffA);
;             PG8_WAIT_V(8); PG8_WAIT_L(0); PG8_BAR; PG8_MMA(0, 0, At, B0); PG8_MMA(0, 1, At, B1); PG8_BAR; PG8_SCHED;
	s_setprio 1
	v_mfma_f32_16x16x32_bf16 v[62:65], v[130:133], v[162:165], v[62:65]
	v_mfma_f32_16x16x32_bf16 v[54:57], v[138:141], v[162:165], v[54:57]
	v_mfma_f32_16x16x32_bf16 v[46:49], v[130:133], v[170:173], v[46:49]
	v_mfma_f32_16x16x32_bf16 v[38:41], v[138:141], v[170:173], v[38:41]
	v_mfma_f32_16x16x32_bf16 v[30:33], v[130:133], v[178:181], v[30:33]
	v_mfma_f32_16x16x32_bf16 v[22:25], v[138:141], v[178:181], v[22:25]
	v_mfma_f32_16x16x32_bf16 v[14:17], v[130:133], v[198:201], v[14:17]
	v_mfma_f32_16x16x32_bf16 v[6:9], v[138:141], v[198:201], v[6:9]
	v_mfma_f32_16x16x32_bf16 v[62:65], v[134:137], v[166:169], v[62:65]
	v_mfma_f32_16x16x32_bf16 v[54:57], v[142:145], v[166:169], v[54:57]
	v_mfma_f32_16x16x32_bf16 v[46:49], v[134:137], v[174:177], v[46:49]
	v_mfma_f32_16x16x32_bf16 v[38:41], v[142:145], v[174:177], v[38:41]
	v_mfma_f32_16x16x32_bf16 v[30:33], v[134:137], v[194:197], v[30:33]
	v_mfma_f32_16x16x32_bf16 v[22:25], v[142:145], v[194:197], v[22:25]
	v_mfma_f32_16x16x32_bf16 v[14:17], v[134:137], v[202:205], v[14:17]
	v_mfma_f32_16x16x32_bf16 v[6:9], v[142:145], v[202:205], v[6:9]
	s_setprio 0
	s_setprio 1
	v_mfma_f32_16x16x32_bf16 v[58:61], v[146:149], v[162:165], v[58:61]
	v_mfma_f32_16x16x32_bf16 v[50:53], v[154:157], v[162:165], v[50:53]
	v_mfma_f32_16x16x32_bf16 v[42:45], v[146:149], v[170:173], v[42:45]
	v_mfma_f32_16x16x32_bf16 v[34:37], v[154:157], v[170:173], v[34:37]
	v_mfma_f32_16x16x32_bf16 v[26:29], v[146:149], v[178:181], v[26:29]
	v_mfma_f32_16x16x32_bf16 v[18:21], v[154:157], v[178:181], v[18:21]
	v_mfma_f32_16x16x32_bf16 v[10:13], v[146:149], v[198:201], v[10:13]
	v_mfma_f32_16x16x32_bf16 v[2:5], v[154:157], v[198:201], v[2:5]
	v_mfma_f32_16x16x32_bf16 v[58:61], v[150:153], v[166:169], v[58:61]
	v_mfma_f32_16x16x32_bf16 v[50:53], v[158:161], v[166:169], v[50:53]
	v_mfma_f32_16x16x32_bf16 v[42:45], v[150:153], v[174:177], v[42:45]
	v_mfma_f32_16x16x32_bf16 v[34:37], v[158:161], v[174:177], v[34:37]
	v_mfma_f32_16x16x32_bf16 v[26:29], v[150:153], v[194:197], v[26:29]
	v_mfma_f32_16x16x32_bf16 v[18:21], v[158:161], v[194:197], v[18:21]
	v_mfma_f32_16x16x32_bf16 v[10:13], v[150:153], v[202:205], v[10:13]
	v_mfma_f32_16x16x32_bf16 v[2:5], v[158:161], v[202:205], v[2:5]
	s_setprio 0
	s_barrier
	s_add_i32 s64, 0, 0x18000
	s_add_i32 s65, 0, 0x1c000
	v_add_u32_e32 v142, s64, v228
	v_add_u32_e32 v158, s65, v228
	ds_read_b128 v[130:133], v142
	ds_read_b128 v[134:137], v142 offset:1024
	ds_read_b128 v[138:141], v142 offset:2048
	ds_read_b128 v[142:145], v142 offset:3072
	ds_read_b128 v[146:149], v158
	ds_read_b128 v[150:153], v158 offset:1024
	ds_read_b128 v[154:157], v158 offset:2048
	ds_read_b128 v[158:161], v158 offset:3072
	s_add_u32 s44, s44, s26
	s_addc_u32 s45, s45, 0
	s_mov_b32 m0, s95
	v_lshl_add_u64 v[238:239], s[44:45], 0, v[182:183]
	ds_read_b128 v[162:165], v230 offset:32768
	ds_read_b128 v[166:169], v230 offset:33792
	ds_read_b128 v[170:173], v230 offset:34816
	ds_read_b128 v[174:177], v230 offset:35840
	ds_read_b128 v[178:181], v230 offset:36864
	ds_read_b128 v[194:197], v230 offset:37888
	ds_read_b128 v[198:201], v230 offset:38912
	ds_read_b128 v[202:205], v230 offset:39936
	global_load_lds_dwordx4 v[238:239], off
	v_lshl_add_u64 v[238:239], s[44:45], 0, v[186:187]
	s_mov_b32 m0, s96
	s_nop 0
	global_load_lds_dwordx4 v[238:239], off
	s_waitcnt vmcnt(8) lgkmcnt(0)
	s_barrier
	s_setprio 1
	v_mfma_f32_16x16x32_bf16 v[126:129], v[130:133], v[162:165], v[126:129]
	v_mfma_f32_16x16x32_bf16 v[122:125], v[138:141], v[162:165], v[122:125]
	v_mfma_f32_16x16x32_bf16 v[110:113], v[130:133], v[170:173], v[110:113]
	v_mfma_f32_16x16x32_bf16 v[102:105], v[138:141], v[170:173], v[102:105]
	v_mfma_f32_16x16x32_bf16 v[94:97], v[130:133], v[178:181], v[94:97]
	v_mfma_f32_16x16x32_bf16 v[86:89], v[138:141], v[178:181], v[86:89]
	v_mfma_f32_16x16x32_bf16 v[78:81], v[130:133], v[198:201], v[78:81]
	v_mfma_f32_16x16x32_bf16 v[70:73], v[138:141], v[198:201], v[70:73]
	v_mfma_f32_16x16x32_bf16 v[126:129], v[134:137], v[166:169], v[126:129]
	v_mfma_f32_16x16x32_bf16 v[122:125], v[142:145], v[166:169], v[122:125]
	v_mfma_f32_16x16x32_bf16 v[110:113], v[134:137], v[174:177], v[110:113]
	v_mfma_f32_16x16x32_bf16 v[102:105], v[142:145], v[174:177], v[102:105]
	v_mfma_f32_16x16x32_bf16 v[94:97], v[134:137], v[194:197], v[94:97]
	v_mfma_f32_16x16x32_bf16 v[86:89], v[142:145], v[194:197], v[86:89]
	v_mfma_f32_16x16x32_bf16 v[78:81], v[134:137], v[202:205], v[78:81]
	v_mfma_f32_16x16x32_bf16 v[70:73], v[142:145], v[202:205], v[70:73]
	s_setprio 0
	s_setprio 1
	v_mfma_f32_16x16x32_bf16 v[118:121], v[146:149], v[162:165], v[118:121]
	v_mfma_f32_16x16x32_bf16 v[114:117], v[154:157], v[162:165], v[114:117]
	v_mfma_f32_16x16x32_bf16 v[106:109], v[146:149], v[170:173], v[106:109]
	v_mfma_f32_16x16x32_bf16 v[98:101], v[154:157], v[170:173], v[98:101]
	v_mfma_f32_16x16x32_bf16 v[90:93], v[146:149], v[178:181], v[90:93]
	v_mfma_f32_16x16x32_bf16 v[82:85], v[154:157], v[178:181], v[82:85]
	v_mfma_f32_16x16x32_bf16 v[74:77], v[146:149], v[198:201], v[74:77]
	v_mfma_f32_16x16x32_bf16 v[66:69], v[154:157], v[198:201], v[66:69]
	v_mfma_f32_16x16x32_bf16 v[118:121], v[150:153], v[166:169], v[118:121]
	v_mfma_f32_16x16x32_bf16 v[114:117], v[158:161], v[166:169], v[114:117]
	v_mfma_f32_16x16x32_bf16 v[106:109], v[150:153], v[174:177], v[106:109]
	v_mfma_f32_16x16x32_bf16 v[98:101], v[158:161], v[174:177], v[98:101]
	v_mfma_f32_16x16x32_bf16 v[90:93], v[150:153], v[194:197], v[90:93]
	v_mfma_f32_16x16x32_bf16 v[82:85], v[158:161], v[194:197], v[82:85]
	v_mfma_f32_16x16x32_bf16 v[74:77], v[150:153], v[202:205], v[74:77]
	v_mfma_f32_16x16x32_bf16 v[66:69], v[158:161], v[202:205], v[66:69]
	s_setprio 0
	s_barrier
; #define PG8_STAGE(bufoff, gbase, voff) do { _Pragma("unroll") for (int _i = 0; _i < 2; ++_i) \
;         __builtin_amdgcn_global_load_lds((const unsigned*)((const char*)(gbase) + (voff)[_i]), (PG8_LAS unsigned*)(lds + (bufoff) + ldsw + _i * 8192), 16, 0, 0); } while (0)
; #define PG8_LDA(dst, b, h) do { _Pragma("unroll") for (int m = 0; m < 4; ++m) _Pragma("unroll") for (int k = 0; k < 2; ++k) dst[m][k] = *(const PG8_LAS bf16x8*)(lds + PG8_SA(b, h) + aoff + m * 2048 + k * 1024); } while (0)
; #define PG8_MMA(ai, bj, At, Bt) do { __builtin_amdgcn_s_setprio(1); _Pragma("unroll") for (int m = 0; m < 4; ++m) _Pragma("unroll") for (int n = 0; n < 2; ++n) _Pragma("unroll") for (int k = 0; k < 2; ++k) \
;         acc[ai][bj][m][n] = __builtin_amdgcn_mfma_f32_16x16x32_bf16(Bt[n][k], At[m][k], acc[ai][bj][m][n], 0, 0, 0); __builtin_amdgcn_s_setprio(0); } while (0)
; #define PG8_WAIT_V(n) asm volatile("s_waitcnt vmcnt(" #n ")" ::: "memory")
; #define PG8_WAIT_L(n) asm volatile("s_waitcnt lgkmcnt(" #n ")" ::: "memory")
; #define PG8_BAR __builtin_amdgcn_s_barrier()
; #define PG8_SCHED __builtin_amdgcn_sched_barrier(0)
; template <class Epi, class Sched, bool ALIGN_EPI = false, bool SP2 = false>
; __device__ __forceinline__ void gemm_phase(PG8_LAS unsigned char* lds, const Gemm g, const Sched& S, const Epi& E) {
;     ...
;             PG8_LDA(At, 1, 1); PG8_STAGE(PG8_SB(1, 0), b3, voffB); PG8_STAGE(PG8_SB(1, 1), b3 + hstep, voffB); PG8_STAGE(PG8_SA(1, 0), a3, voffA);
;             PG8_WAIT_V(8); PG8_WAIT_L(0); PG8_BAR; PG8_MMA(1, 0, At, B0); PG8_MMA(1, 1, At, B1); PG8_BAR; PG8_SCHED;
;     ...
;         if constexpr (ALIGN_EPI) { if (wr == 0) PG8_BAR; }
;         if constexpr (!Epi::AFTER_DRAIN) { E(acc, cur, wr, wc, fr, fq); S.done(cur); }
	s_add_i32 s44, s64, s92
	v_lshl_add_u64 v[206:207], v[206:207], 0, s[34:35]
	s_mov_b32 m0, s44
	ds_read_b128 v[162:165], v230 offset:49152
	ds_read_b128 v[166:169], v230 offset:50176
	ds_read_b128 v[170:173], v230 offset:51200
	ds_read_b128 v[174:177], v230 offset:52224
	ds_read_b128 v[178:181], v230 offset:53248
	ds_read_b128 v[194:197], v230 offset:54272
	ds_read_b128 v[198:201], v230 offset:55296
	ds_read_b128 v[202:205], v230 offset:56320
	global_load_lds_dwordx4 v[206:207], off
	v_lshl_add_u64 v[206:207], v[208:209], 0, s[34:35]
	s_add_i32 m0, s44, 0x2000
	s_add_i32 s44, s65, s92
	global_load_lds_dwordx4 v[206:207], off
	v_lshl_add_u64 v[206:207], v[210:211], 0, s[34:35]
	s_mov_b32 m0, s44
	s_nop 0
	global_load_lds_dwordx4 v[206:207], off
	v_lshl_add_u64 v[206:207], v[232:233], 0, s[34:35]
	s_add_i32 m0, s44, 0x2000
	s_nop 0
	global_load_lds_dwordx4 v[206:207], off
	v_lshl_add_u64 v[206:207], v[234:235], 0, s[34:35]
	s_mov_b32 m0, s97
	s_nop 0
	global_load_lds_dwordx4 v[206:207], off
	v_lshl_add_u64 v[206:207], v[236:237], 0, s[34:35]
	s_mov_b32 m0, s98
	s_nop 0
	global_load_lds_dwordx4 v[206:207], off
	s_waitcnt vmcnt(8) lgkmcnt(0)
	s_barrier
	s_setprio 1
	v_mfma_f32_16x16x32_bf16 v[62:65], v[130:133], v[162:165], v[62:65]
	v_mfma_f32_16x16x32_bf16 v[54:57], v[138:141], v[162:165], v[54:57]
	v_mfma_f32_16x16x32_bf16 v[46:49], v[130:133], v[170:173], v[46:49]
	v_mfma_f32_16x16x32_bf16 v[38:41], v[138:141], v[170:173], v[38:41]
	v_mfma_f32_16x16x32_bf16 v[30:33], v[130:133], v[178:181], v[30:33]
	v_mfma_f32_16x16x32_bf16 v[22:25], v[138:141], v[178:181], v[22:25]
	v_mfma_f32_16x16x32_bf16 v[14:17], v[130:133], v[198:201], v[14:17]
	v_mfma_f32_16x16x32_bf16 v[6:9], v[138:141], v[198:201], v[6:9]
	v_mfma_f32_16x16x32_bf16 v[62:65], v[134:137], v[166:169], v[62:65]
	v_mfma_f32_16x16x32_bf16 v[54:57], v[142:145], v[166:169], v[54:57]
	v_mfma_f32_16x16x32_bf16 v[46:49], v[134:137], v[174:177], v[46:49]
	v_mfma_f32_16x16x32_bf16 v[38:41], v[142:145], v[174:177], v[38:41]
	v_mfma_f32_16x16x32_bf16 v[30:33], v[134:137], v[194:197], v[30:33]
	v_mfma_f32_16x16x32_bf16 v[22:25], v[142:145], v[194:197], v[22:25]
	v_mfma_f32_16x16x32_bf16 v[14:17], v[134:137], v[202:205], v[14:17]
	v_mfma_f32_16x16x32_bf16 v[6:9], v[142:145], v[202:205], v[6:9]
	s_setprio 0
	s_setprio 1
	v_mfma_f32_16x16x32_bf16 v[58:61], v[146:149], v[162:165], v[58:61]
	v_mfma_f32_16x16x32_bf16 v[50:53], v[154:157], v[162:165], v[50:53]
	v_mfma_f32_16x16x32_bf16 v[42:45], v[146:149], v[170:173], v[42:45]
	v_mfma_f32_16x16x32_bf16 v[34:37], v[154:157], v[170:173], v[34:37]
	v_mfma_f32_16x16x32_bf16 v[26:29], v[146:149], v[178:181], v[26:29]
	v_mfma_f32_16x16x32_bf16 v[18:21], v[154:157], v[178:181], v[18:21]
	v_mfma_f32_16x16x32_bf16 v[10:13], v[146:149], v[198:201], v[10:13]
	v_mfma_f32_16x16x32_bf16 v[2:5], v[154:157], v[198:201], v[2:5]
	v_mfma_f32_16x16x32_bf16 v[58:61], v[150:153], v[166:169], v[58:61]
	v_mfma_f32_16x16x32_bf16 v[50:53], v[158:161], v[166:169], v[50:53]
	v_mfma_f32_16x16x32_bf16 v[42:45], v[150:153], v[174:177], v[42:45]
	v_mfma_f32_16x16x32_bf16 v[34:37], v[158:161], v[174:177], v[34:37]
	v_mfma_f32_16x16x32_bf16 v[26:29], v[150:153], v[194:197], v[26:29]
	v_mfma_f32_16x16x32_bf16 v[18:21], v[158:161], v[194:197], v[18:21]
	v_mfma_f32_16x16x32_bf16 v[10:13], v[150:153], v[202:205], v[10:13]
	v_mfma_f32_16x16x32_bf16 v[2:5], v[158:161], v[202:205], v[2:5]
	s_setprio 0
	s_barrier
	s_add_u32 s42, s42, 0x100
	s_addc_u32 s43, s43, 0
	s_add_u32 s17, s17, 0x100
	s_addc_u32 s60, s60, 0
	s_cmp_ge_u32 s61, s4
	s_mov_b32 s44, s61
	s_cbranch_scc0 .LBB0_441
	s_and_b64 vcc, exec, s[36:37]
	s_cbranch_vccz .LBB0_445
	s_barrier
	s_cmp_lt_i32 s0, 2
	s_mov_b64 s[42:43], -1
	s_cbranch_scc0 .LBB0_446
